# phase0 S5-constant CM table loads issued together (was 16 serialised round trips)
# speedup vs baseline: 1.0377x; 1.0096x over previous
.LBB0_33:
	s_or_b64 exec, exec, s[26:27]
	s_waitcnt vmcnt(0)
	v_cvt_f64_f32_e32 v[12:13], v1
	s_mov_b32 s18, 0x652b82fe
	v_mul_f64 v[6:7], v[6:7], v[12:13]
	s_mov_b32 s19, 0x3ff71547
	v_mul_f64 v[18:19], v[6:7], s[18:19]
	s_mov_b32 s18, 0xfefa39ef
	v_rndne_f64_e32 v[18:19], v[18:19]
	s_mov_b32 s19, 0xbfe62e42
	v_fma_f64 v[82:83], s[18:19], v[18:19], v[6:7]
	s_mov_b32 s18, 0x3b39803f
	s_mov_b32 s19, 0xbc7abc9e
	v_fmac_f64_e32 v[82:83], s[18:19], v[18:19]
	s_mov_b32 s18, 0x6a5dcb37
	v_mov_b64_e32 v[84:85], v[30:31]
	s_mov_b32 s19, 0x3e5ade15
	v_fmac_f64_e32 v[84:85], s[18:19], v[82:83]
	v_mov_b64_e32 v[88:89], v[32:33]
	v_fmac_f64_e32 v[88:89], v[82:83], v[84:85]
	v_mov_b64_e32 v[84:85], v[34:35]
	v_fmac_f64_e32 v[84:85], v[82:83], v[88:89]
	v_mov_b64_e32 v[88:89], v[36:37]
	v_fmac_f64_e32 v[88:89], v[82:83], v[84:85]
	v_mov_b64_e32 v[84:85], v[38:39]
	v_mov_b32_e32 v41, v43
	v_fmac_f64_e32 v[84:85], v[82:83], v[88:89]
	v_mov_b64_e32 v[88:89], v[40:41]
	v_mov_b32_e32 v47, v49
	v_fmac_f64_e32 v[88:89], v[82:83], v[84:85]
	v_mov_b64_e32 v[84:85], v[46:47]
	v_fmac_f64_e32 v[84:85], v[82:83], v[88:89]
	v_mov_b64_e32 v[88:89], v[52:53]
	v_fmac_f64_e32 v[88:89], v[82:83], v[84:85]
	v_mov_b64_e32 v[84:85], v[54:55]
	s_mov_b32 s18, 0
	v_fmac_f64_e32 v[84:85], v[82:83], v[88:89]
	s_mov_b32 s19, 0x40900000
	v_fma_f64 v[84:85], v[82:83], v[84:85], 1.0
	v_cmp_nlt_f64_e32 vcc, s[18:19], v[6:7]
	s_mov_b32 s18, 0
	v_fma_f64 v[82:83], v[82:83], v[84:85], 1.0
	v_cvt_i32_f64_e32 v1, v[18:19]
	s_mov_b32 s19, 0xc090cc00
	v_ldexp_f64 v[18:19], v[82:83], v1
	v_cmp_ngt_f64_e64 s[26:27], s[18:19], v[6:7]
	s_mov_b32 s18, 0x9037ab78
	v_cndmask_b32_e32 v1, v99, v19, vcc
	s_and_b64 vcc, s[26:27], vcc
	s_mov_b32 s19, 0x3e21eeb6
	v_cndmask_b32_e32 v6, 0, v18, vcc
	v_mul_f64 v[18:19], v[8:9], v[8:9]
	v_mov_b64_e32 v[90:91], s[18:19]
	s_mov_b32 s42, 0xa17f65f6
	v_mul_f64 v[82:83], v[18:19], 0.5
	v_fma_f64 v[92:93], s[24:25], v[18:19], v[90:91]
	s_mov_b32 s43, 0xbe927e4f
	s_mov_b32 s44, 0x19f4ec90
	v_add_f64 v[84:85], -v[82:83], 1.0
	v_fma_f64 v[92:93], v[18:19], v[92:93], s[42:43]
	s_mov_b32 s45, 0x3efa01a0
	s_mov_b32 s46, 0x16c16967
	v_cndmask_b32_e64 v7, 0, v1, s[26:27]
	v_add_f64 v[88:89], -v[84:85], 1.0
	v_fma_f64 v[92:93], v[18:19], v[92:93], s[44:45]
	s_mov_b32 s47, 0xbf56c16c
	v_readlane_b32 s26, v253, 13
	v_add_f64 v[82:83], v[88:89], -v[82:83]
	v_fma_f64 v[92:93], v[18:19], v[92:93], s[46:47]
	v_readlane_b32 s27, v253, 14
	s_mov_b32 s26, s50
	v_mul_f64 v[88:89], v[18:19], v[18:19]
	v_fma_f64 v[92:93], v[18:19], v[92:93], s[26:27]
	v_fma_f64 v[82:83], v[8:9], -v[10:11], v[82:83]
	s_mov_b32 s18, 0xb42fdfa7
	v_fmac_f64_e32 v[82:83], v[88:89], v[92:93]
	s_mov_b32 s19, 0xbe5ae600
	v_add_f64 v[82:83], v[84:85], v[82:83]
	v_mov_b64_e32 v[84:85], s[18:19]
	s_mov_b32 s56, 0x796cde01
	v_fma_f64 v[88:89], s[52:53], v[18:19], v[84:85]
	s_mov_b32 s57, 0x3ec71de3
	s_mov_b32 s58, 0x19e83e5c
	v_fma_f64 v[88:89], v[18:19], v[88:89], s[56:57]
	s_mov_b32 s59, 0xbf2a01a0
	s_mov_b32 s18, 0x11110bb3
	v_fma_f64 v[88:89], v[18:19], v[88:89], s[58:59]
	s_mov_b32 s19, 0x3f811111
	v_fma_f64 v[88:89], v[18:19], v[88:89], s[18:19]
	v_mul_f64 v[92:93], v[8:9], -v[18:19]
	v_mul_f64 v[94:95], v[10:11], 0.5
	v_fmac_f64_e32 v[94:95], v[92:93], v[88:89]
	v_fma_f64 v[10:11], v[18:19], v[94:95], -v[10:11]
	v_fmac_f64_e32 v[10:11], s[50:51], v[92:93]
	v_add_f64 v[8:9], v[8:9], -v[10:11]
	v_xor_b32_e32 v1, 0x80000000, v9
	v_and_b32_e32 v9, 1, v64
	v_cmp_eq_u32_e32 vcc, 0, v9
	v_mul_f64 v[18:19], v[14:15], v[14:15]
	v_fmac_f64_e32 v[90:91], s[24:25], v[18:19]
	v_cndmask_b32_e32 v8, v8, v82, vcc
	v_cndmask_b32_e32 v1, v1, v83, vcc
	v_mul_f64 v[82:83], v[18:19], 0.5
	v_add_f64 v[88:89], -v[82:83], 1.0
	v_fma_f64 v[90:91], v[18:19], v[90:91], s[42:43]
	v_add_f64 v[92:93], -v[88:89], 1.0
	v_fma_f64 v[90:91], v[18:19], v[90:91], s[44:45]
	v_add_f64 v[82:83], v[92:93], -v[82:83]
	v_fma_f64 v[90:91], v[18:19], v[90:91], s[46:47]
	v_fmac_f64_e32 v[84:85], s[52:53], v[18:19]
	v_mul_f64 v[92:93], v[18:19], v[18:19]
	v_fma_f64 v[90:91], v[18:19], v[90:91], s[26:27]
	v_fma_f64 v[82:83], v[14:15], -v[16:17], v[82:83]
	v_fma_f64 v[84:85], v[18:19], v[84:85], s[56:57]
	v_fmac_f64_e32 v[82:83], v[92:93], v[90:91]
	v_fma_f64 v[84:85], v[18:19], v[84:85], s[58:59]
	v_add_f64 v[82:83], v[88:89], v[82:83]
	v_fma_f64 v[84:85], v[18:19], v[84:85], s[18:19]
	v_mul_f64 v[88:89], v[14:15], -v[18:19]
	v_mul_f64 v[90:91], v[16:17], 0.5
	v_lshlrev_b32_e32 v9, 30, v64
	v_fmac_f64_e32 v[90:91], v[88:89], v[84:85]
	v_bitop3_b32 v1, v1, v9, s7 bitop3:0x78
	v_cmp_class_f64_e64 vcc, v[4:5], s8
	v_fma_f64 v[16:17], v[18:19], v[90:91], -v[16:17]
	v_fmac_f64_e32 v[16:17], s[50:51], v[88:89]
	v_cndmask_b32_e32 v9, v107, v1, vcc
	v_and_b32_e32 v1, 1, v86
	s_mov_b32 s17, s27
	v_add_f64 v[14:15], v[14:15], -v[16:17]
	v_cmp_eq_u32_e64 s[26:27], 0, v1
	v_writelane_b32 v253, s16, 13
	v_cndmask_b32_e32 v8, 0, v8, vcc
	v_cndmask_b32_e64 v1, v82, v14, s[26:27]
	v_lshlrev_b32_e32 v14, 30, v86
	v_cndmask_b32_e64 v4, v83, v15, s[26:27]
	v_xor_b32_e32 v5, v14, v5
	v_bitop3_b32 v5, v4, v5, s7 bitop3:0x78
	v_cndmask_b32_e32 v4, 0, v1, vcc
	v_cndmask_b32_e32 v5, v107, v5, vcc
	v_writelane_b32 v253, s17, 14
	v_mul_f64 v[4:5], v[6:7], v[4:5]
	v_lshlrev_b32_e32 v0, 1, v0
	v_mul_f64 v[10:11], v[6:7], v[8:9]
	v_mul_f64 v[14:15], v[2:3], v[2:3]
	v_fma_f64 v[6:7], v[6:7], v[8:9], -1.0
	v_mul_f64 v[8:9], v[4:5], v[2:3]
	v_ashrrev_i32_e32 v1, 31, v0
	v_readlane_b32 s18, v253, 15
	v_fmac_f64_e32 v[8:9], v[6:7], v[12:13]
	v_mul_f64 v[2:3], v[6:7], v[2:3]
	v_lshlrev_b64 v[0:1], 2, v[0:1]
	v_readlane_b32 s19, v253, 16
	v_fmac_f64_e32 v[14:15], v[12:13], v[12:13]
	v_fma_f64 v[2:3], v[4:5], v[12:13], -v[2:3]
	v_lshl_add_u64 v[6:7], s[18:19], 0, v[0:1]
	v_div_scale_f64 v[12:13], s[18:19], v[14:15], v[14:15], v[8:9]
	v_rcp_f64_e32 v[18:19], v[12:13]
	v_cvt_f32_f64_e32 v16, v[10:11]
	v_cvt_f32_f64_e32 v17, v[4:5]
	global_store_dwordx2 v[6:7], v[16:17], off
	v_fma_f64 v[82:83], -v[12:13], v[18:19], 1.0
	v_fmac_f64_e32 v[18:19], v[18:19], v[82:83]
	v_mul_f64 v[6:7], v[4:5], v[4:5]
	v_fma_f64 v[82:83], -v[12:13], v[18:19], 1.0
	v_fma_f64 v[6:7], v[10:11], v[10:11], -v[6:7]
	v_add_f64 v[10:11], v[10:11], v[10:11]
	v_fmac_f64_e32 v[18:19], v[18:19], v[82:83]
	v_div_scale_f64 v[82:83], vcc, v[8:9], v[14:15], v[8:9]
	v_mul_f64 v[4:5], v[10:11], v[4:5]
	v_mul_f64 v[84:85], v[82:83], v[18:19]
	v_mul_f64 v[10:11], v[4:5], v[4:5]
	v_fma_f64 v[12:13], -v[12:13], v[84:85], v[82:83]
	v_fma_f64 v[10:11], v[6:7], v[6:7], -v[10:11]
	v_add_f64 v[6:7], v[6:7], v[6:7]
	v_div_fmas_f64 v[12:13], v[12:13], v[18:19], v[84:85]
	v_mul_f64 v[4:5], v[4:5], v[6:7]
	v_div_fixup_f64 v[82:83], v[12:13], v[14:15], v[8:9]
	v_div_scale_f64 v[8:9], s[18:19], v[14:15], v[14:15], v[2:3]
	v_mul_f64 v[6:7], v[4:5], v[4:5]
	v_rcp_f64_e32 v[12:13], v[8:9]
	v_fma_f64 v[6:7], v[10:11], v[10:11], -v[6:7]
	v_add_f64 v[10:11], v[10:11], v[10:11]
	v_mul_f64 v[4:5], v[4:5], v[10:11]
	v_mul_f64 v[10:11], v[4:5], v[4:5]
	v_fma_f64 v[10:11], v[6:7], v[6:7], -v[10:11]
	v_add_f64 v[6:7], v[6:7], v[6:7]
	v_fma_f64 v[18:19], -v[8:9], v[12:13], 1.0
	v_mul_f64 v[4:5], v[4:5], v[6:7]
	v_fmac_f64_e32 v[12:13], v[12:13], v[18:19]
	v_mul_f64 v[6:7], v[4:5], v[4:5]
	v_fma_f64 v[18:19], -v[8:9], v[12:13], 1.0
	v_fma_f64 v[6:7], v[10:11], v[10:11], -v[6:7]
	v_add_f64 v[10:11], v[10:11], v[10:11]
	v_fmac_f64_e32 v[12:13], v[12:13], v[18:19]
	v_div_scale_f64 v[18:19], vcc, v[2:3], v[14:15], v[2:3]
	v_mul_f64 v[4:5], v[4:5], v[10:11]
	v_mul_f64 v[84:85], v[18:19], v[12:13]
	v_mul_f64 v[10:11], v[4:5], v[4:5]
	v_fma_f64 v[8:9], -v[8:9], v[84:85], v[18:19]
	v_fma_f64 v[10:11], v[6:7], v[6:7], -v[10:11]
	v_add_f64 v[6:7], v[6:7], v[6:7]
	v_div_fmas_f64 v[8:9], v[8:9], v[12:13], v[84:85]
	v_div_fixup_f64 v[84:85], v[8:9], v[14:15], v[2:3]
	v_mul_f64 v[2:3], v[4:5], v[6:7]
	v_mul_f64 v[4:5], v[2:3], v[2:3]
	v_add_f64 v[16:17], v[10:11], v[10:11]
	v_readlane_b32 s18, v253, 17
	v_fma_f64 v[4:5], v[10:11], v[10:11], -v[4:5]
	s_lshr_b32 s15, s15, 1
	v_readlane_b32 s19, v253, 18
	v_mul_f64 v[2:3], v[2:3], v[16:17]
	v_mul_f64 v[6:7], v[4:5], v[4:5]
	v_add_f64 v[4:5], v[4:5], v[4:5]
	s_and_b32 s15, s15, 0x7fffffe0
	s_load_dwordx16 s[56:71], s[0:1], 0x80
	v_lshl_add_u64 v[0:1], s[18:19], 0, v[0:1]
	v_fma_f64 v[6:7], -v[2:3], v[2:3], v[6:7]
	v_mul_f64 v[2:3], v[2:3], v[4:5]
	s_lshl_b64 s[18:19], s[22:23], 12
	s_or_b32 s22, s15, s16
	v_cvt_f32_f64_e32 v3, v[2:3]
	v_cvt_f32_f64_e32 v2, v[6:7]
	s_lshl_b64 s[26:27], s[22:23], 10
	global_store_dwordx2 v[0:1], v[2:3], off
	v_lshl_add_u64 v[0:1], s[26:27], 0, v[22:23]
	v_lshlrev_b64 v[0:1], 2, v[0:1]
	s_waitcnt lgkmcnt(0)
	v_lshl_add_u64 v[4:5], s[66:67], 0, v[0:1]
	v_lshl_add_u64 v[92:93], s[64:65], 0, v[0:1]
	global_load_dwordx4 v[0:3], v[4:5], off offset:48
	global_load_dwordx4 v[8:11], v[4:5], off offset:32
	global_load_dwordx4 v[16:19], v[4:5], off offset:16
	s_nop 0
	global_load_dwordx4 v[4:7], v[4:5], off
	v_lshl_add_u64 v[86:87], v[58:59], 0, s[18:19]
	s_cmp_lg_u32 s14, 0
	s_waitcnt vmcnt(0)
	v_cvt_f64_f32_e32 v[96:97], v7
	v_cvt_f64_f32_e32 v[112:113], v6
	v_cvt_f64_f32_e32 v[114:115], v5
	v_cvt_f64_f32_e32 v[116:117], v4
	global_load_dwordx4 v[4:7], v[92:93], off offset:48
	global_load_dwordx4 v[12:15], v[92:93], off offset:32
	global_load_dwordx4 v[88:91], v[92:93], off offset:16
	s_nop 0
	global_load_dwordx4 v[92:95], v[92:93], off
	v_mul_f64 v[118:119], v[82:83], v[116:117]
	v_mul_f64 v[116:117], v[84:85], v[116:117]
	s_waitcnt vmcnt(0)
	v_cvt_f64_f32_e32 v[122:123], v93
	v_cvt_f64_f32_e32 v[92:93], v92
	v_fmac_f64_e32 v[118:119], v[84:85], v[92:93]
	v_cvt_f32_f64_e32 v41, v[118:119]
	v_mul_f64 v[118:119], v[82:83], v[114:115]
	v_fmac_f64_e32 v[118:119], v[84:85], v[122:123]
	v_cvt_f64_f32_e32 v[120:121], v95
	v_cvt_f64_f32_e32 v[94:95], v94
	v_cvt_f32_f64_e32 v47, v[118:119]
	v_mul_f64 v[118:119], v[82:83], v[112:113]
	v_mul_f64 v[112:113], v[84:85], v[112:113]
	v_fmac_f64_e32 v[118:119], v[84:85], v[94:95]
	v_mul_f64 v[114:115], v[84:85], v[114:115]
	v_fma_f64 v[94:95], v[82:83], v[94:95], -v[112:113]
	v_fma_f64 v[92:93], v[82:83], v[92:93], -v[116:117]
	v_fma_f64 v[114:115], v[82:83], v[122:123], -v[114:115]
	v_cvt_f32_f64_e32 v117, v[94:95]
	v_cvt_f64_f32_e32 v[94:95], v17
	v_cvt_f64_f32_e32 v[16:17], v16
	v_cvt_f32_f64_e32 v64, v[118:119]
	v_mul_f64 v[118:119], v[84:85], v[96:97]
	v_cvt_f32_f64_e32 v109, v[114:115]
	v_cvt_f32_f64_e32 v110, v[92:93]
	v_mul_f64 v[92:93], v[82:83], v[96:97]
	v_mul_f64 v[96:97], v[82:83], v[16:17]
	v_cvt_f64_f32_e32 v[114:115], v89
	v_cvt_f64_f32_e32 v[88:89], v88
	v_fmac_f64_e32 v[96:97], v[84:85], v[88:89]
	v_fma_f64 v[112:113], v[82:83], v[120:121], -v[118:119]
	v_fmac_f64_e32 v[92:93], v[84:85], v[120:121]
	v_cvt_f32_f64_e32 v119, v[96:97]
	v_mul_f64 v[96:97], v[82:83], v[94:95]
	v_cvt_f32_f64_e32 v118, v[92:93]
	v_cvt_f64_f32_e32 v[92:93], v19
	v_cvt_f64_f32_e32 v[18:19], v18
	v_fmac_f64_e32 v[96:97], v[84:85], v[114:115]
	v_cvt_f32_f64_e32 v116, v[112:113]
	v_cvt_f64_f32_e32 v[112:113], v91
	v_cvt_f64_f32_e32 v[90:91], v90
	v_cvt_f32_f64_e32 v120, v[96:97]
	v_mul_f64 v[96:97], v[82:83], v[18:19]
	v_fmac_f64_e32 v[96:97], v[84:85], v[90:91]
	v_cvt_f32_f64_e32 v121, v[96:97]
	v_mul_f64 v[94:95], v[84:85], v[94:95]
	v_mul_f64 v[16:17], v[84:85], v[16:17]
	v_mul_f64 v[96:97], v[84:85], v[92:93]
	v_mul_f64 v[18:19], v[84:85], v[18:19]
	v_fma_f64 v[18:19], v[82:83], v[90:91], -v[18:19]
	v_fma_f64 v[90:91], v[82:83], v[112:113], -v[96:97]
	v_fma_f64 v[16:17], v[82:83], v[88:89], -v[16:17]
	v_fma_f64 v[88:89], v[82:83], v[114:115], -v[94:95]
	v_cvt_f32_f64_e32 v88, v[88:89]
	v_cvt_f32_f64_e32 v16, v[16:17]
	v_cvt_f32_f64_e32 v17, v[90:91]
	v_cvt_f32_f64_e32 v18, v[18:19]
	v_cvt_pk_bf16_f32 v19, v18, v17
	v_cvt_pk_bf16_f32 v18, v16, v88
	v_cvt_pk_bf16_f32 v17, v117, v116
	v_cvt_pk_bf16_f32 v16, v110, v109
	global_store_dwordx4 v[86:87], v[16:19], off
	v_cvt_f64_f32_e32 v[90:91], v15
	v_cvt_f64_f32_e32 v[14:15], v14
	v_mul_f64 v[16:17], v[82:83], v[92:93]
	v_fmac_f64_e32 v[16:17], v[84:85], v[112:113]
	v_cvt_f32_f64_e32 v16, v[16:17]
	v_cvt_pk_bf16_f32 v19, v121, v16
	v_cvt_pk_bf16_f32 v18, v119, v120
	v_cvt_pk_bf16_f32 v17, v64, v118
	v_cvt_pk_bf16_f32 v16, v41, v47
	global_store_dwordx4 v[86:87], v[16:19], off offset:1024
	v_cvt_f64_f32_e32 v[92:93], v13
	v_cvt_f64_f32_e32 v[12:13], v12
	v_cvt_f64_f32_e32 v[18:19], v9
	v_cvt_f64_f32_e32 v[8:9], v8
	v_mul_f64 v[88:89], v[82:83], v[8:9]
	v_fmac_f64_e32 v[88:89], v[84:85], v[12:13]
	v_cvt_f32_f64_e32 v41, v[88:89]
	v_mul_f64 v[88:89], v[82:83], v[18:19]
	v_cvt_f64_f32_e32 v[16:17], v11
	v_cvt_f64_f32_e32 v[10:11], v10
	v_fmac_f64_e32 v[88:89], v[84:85], v[92:93]
	v_cvt_f32_f64_e32 v47, v[88:89]
	v_mul_f64 v[88:89], v[82:83], v[10:11]
	v_fmac_f64_e32 v[88:89], v[84:85], v[14:15]
	v_mul_f64 v[10:11], v[84:85], v[10:11]
	v_cvt_f32_f64_e32 v64, v[88:89]
	v_mul_f64 v[18:19], v[84:85], v[18:19]
	v_mul_f64 v[8:9], v[84:85], v[8:9]
	v_mul_f64 v[88:89], v[84:85], v[16:17]
	v_fma_f64 v[10:11], v[82:83], v[14:15], -v[10:11]
	v_fma_f64 v[14:15], v[82:83], v[90:91], -v[88:89]
	v_fma_f64 v[8:9], v[82:83], v[12:13], -v[8:9]
	v_fma_f64 v[12:13], v[82:83], v[92:93], -v[18:19]
	v_cvt_f32_f64_e32 v89, v[10:11]
	v_cvt_f64_f32_e32 v[10:11], v1
	v_cvt_f64_f32_e32 v[0:1], v0
	v_cvt_f32_f64_e32 v18, v[12:13]
	v_cvt_f32_f64_e32 v19, v[8:9]
	v_mul_f64 v[8:9], v[82:83], v[16:17]
	v_mul_f64 v[12:13], v[82:83], v[0:1]
	v_cvt_f64_f32_e32 v[16:17], v5
	v_cvt_f64_f32_e32 v[4:5], v4
	v_fmac_f64_e32 v[12:13], v[84:85], v[4:5]
	v_fmac_f64_e32 v[8:9], v[84:85], v[90:91]
	v_cvt_f32_f64_e32 v91, v[12:13]
	v_mul_f64 v[12:13], v[82:83], v[10:11]
	v_cvt_f32_f64_e32 v90, v[8:9]
	v_cvt_f64_f32_e32 v[8:9], v3
	v_cvt_f64_f32_e32 v[2:3], v2
	v_fmac_f64_e32 v[12:13], v[84:85], v[16:17]
	v_cvt_f32_f64_e32 v88, v[14:15]
	v_cvt_f64_f32_e32 v[14:15], v7
	v_cvt_f64_f32_e32 v[6:7], v6
	v_cvt_f32_f64_e32 v92, v[12:13]
	v_mul_f64 v[12:13], v[82:83], v[2:3]
	v_fmac_f64_e32 v[12:13], v[84:85], v[6:7]
	v_cvt_f32_f64_e32 v93, v[12:13]
	v_mul_f64 v[10:11], v[84:85], v[10:11]
	v_mul_f64 v[0:1], v[84:85], v[0:1]
	v_mul_f64 v[12:13], v[84:85], v[8:9]
	v_mul_f64 v[2:3], v[84:85], v[2:3]
	v_fma_f64 v[2:3], v[82:83], v[6:7], -v[2:3]
	v_fma_f64 v[6:7], v[82:83], v[14:15], -v[12:13]
	v_fma_f64 v[0:1], v[82:83], v[4:5], -v[0:1]
	v_fma_f64 v[4:5], v[82:83], v[16:17], -v[10:11]
	v_cvt_f32_f64_e32 v4, v[4:5]
	v_cvt_f32_f64_e32 v0, v[0:1]
	v_cvt_f32_f64_e32 v1, v[6:7]
	v_cvt_f32_f64_e32 v2, v[2:3]
	v_cvt_pk_bf16_f32 v3, v2, v1
	v_cvt_pk_bf16_f32 v2, v0, v4
	v_cvt_pk_bf16_f32 v1, v89, v88
	v_cvt_pk_bf16_f32 v0, v19, v18
	global_store_dwordx4 v[86:87], v[0:3], off offset:16
	s_nop 1
	v_mul_f64 v[0:1], v[82:83], v[8:9]
	v_fmac_f64_e32 v[0:1], v[84:85], v[14:15]
	v_cvt_f32_f64_e32 v0, v[0:1]
	v_cvt_pk_bf16_f32 v3, v93, v0
	v_cvt_pk_bf16_f32 v2, v91, v92
	v_cvt_pk_bf16_f32 v1, v64, v90
	v_cvt_pk_bf16_f32 v0, v41, v47
	global_store_dwordx4 v[86:87], v[0:3], off offset:1040
	s_cbranch_scc1 .LBB0_35
	s_load_dwordx16 s[56:71], s[0:1], 0x80
	v_lshl_add_u64 v[0:1], s[26:27], 0, v[20:21]
	v_lshlrev_b64 v[0:1], 2, v[0:1]
	s_lshl_b64 s[14:15], s[22:23], 13
	s_waitcnt lgkmcnt(0)
	v_lshl_add_u64 v[4:5], s[70:71], 0, v[0:1]
	v_lshl_add_u64 v[2:3], s[68:69], 0, v[0:1]
	global_load_dword v128, v[4:5], off
	global_load_dword v129, v[2:3], off
	global_load_dword v130, v[4:5], off offset:256
	global_load_dword v131, v[2:3], off offset:256
	global_load_dword v132, v[4:5], off offset:512
	global_load_dword v133, v[2:3], off offset:512
	global_load_dword v134, v[4:5], off offset:768
	global_load_dword v135, v[2:3], off offset:768
	global_load_dword v136, v[4:5], off offset:1024
	global_load_dword v137, v[2:3], off offset:1024
	global_load_dword v138, v[4:5], off offset:1280
	global_load_dword v139, v[2:3], off offset:1280
	global_load_dword v140, v[4:5], off offset:1536
	global_load_dword v141, v[2:3], off offset:1536
	global_load_dword v142, v[4:5], off offset:1792
	global_load_dword v143, v[2:3], off offset:1792
	global_load_dword v144, v[4:5], off offset:2048
	global_load_dword v145, v[2:3], off offset:2048
	global_load_dword v146, v[4:5], off offset:2304
	global_load_dword v147, v[2:3], off offset:2304
	global_load_dword v148, v[4:5], off offset:2560
	global_load_dword v149, v[2:3], off offset:2560
	global_load_dword v150, v[4:5], off offset:2816
	global_load_dword v151, v[2:3], off offset:2816
	global_load_dword v152, v[4:5], off offset:3072
	global_load_dword v153, v[2:3], off offset:3072
	global_load_dword v154, v[4:5], off offset:3328
	global_load_dword v155, v[2:3], off offset:3328
	global_load_dword v156, v[4:5], off offset:3584
	global_load_dword v157, v[2:3], off offset:3584
	global_load_dword v158, v[4:5], off offset:3840
	global_load_dword v159, v[2:3], off offset:3840
	v_lshl_add_u64 v[0:1], v[60:61], 0, s[14:15]
	s_movk_i32 s14, 0x1000
	s_waitcnt vmcnt(0)
	v_cvt_pk_bf16_f32 v6, v129, -v128
	global_store_dword v[0:1], v6, off
	v_cvt_pk_bf16_f32 v6, v131, -v130
	global_store_dword v[0:1], v6, off offset:256
	v_cvt_pk_bf16_f32 v6, v133, -v132
	global_store_dword v[0:1], v6, off offset:512
	v_cvt_pk_bf16_f32 v6, v135, -v134
	global_store_dword v[0:1], v6, off offset:768
	v_cvt_pk_bf16_f32 v6, v137, -v136
	global_store_dword v[0:1], v6, off offset:1024
	v_cvt_pk_bf16_f32 v6, v139, -v138
	global_store_dword v[0:1], v6, off offset:1280
	v_cvt_pk_bf16_f32 v6, v141, -v140
	global_store_dword v[0:1], v6, off offset:1536
	v_cvt_pk_bf16_f32 v6, v143, -v142
	global_store_dword v[0:1], v6, off offset:1792
	v_cvt_pk_bf16_f32 v6, v145, -v144
	global_store_dword v[0:1], v6, off offset:2048
	v_cvt_pk_bf16_f32 v6, v147, -v146
	global_store_dword v[0:1], v6, off offset:2304
	v_cvt_pk_bf16_f32 v6, v149, -v148
	global_store_dword v[0:1], v6, off offset:2560
	v_cvt_pk_bf16_f32 v6, v151, -v150
	global_store_dword v[0:1], v6, off offset:2816
	v_cvt_pk_bf16_f32 v6, v153, -v152
	global_store_dword v[0:1], v6, off offset:3072
	v_cvt_pk_bf16_f32 v6, v155, -v154
	global_store_dword v[0:1], v6, off offset:3328
	v_cvt_pk_bf16_f32 v6, v157, -v156
	global_store_dword v[0:1], v6, off offset:3584
	v_cvt_pk_bf16_f32 v6, v159, -v158
	global_store_dword v[0:1], v6, off offset:3840
	v_add_co_u32_e32 v0, vcc, s14, v0
	s_nop 1
	v_addc_co_u32_e32 v1, vcc, 0, v1, vcc
	global_store_dword v[0:1], v111, off
	global_store_dword v[0:1], v111, off offset:256
	global_store_dword v[0:1], v111, off offset:512
	global_store_dword v[0:1], v111, off offset:768
	global_store_dword v[0:1], v111, off offset:1024
	global_store_dword v[0:1], v111, off offset:1280
	global_store_dword v[0:1], v111, off offset:1536
	global_store_dword v[0:1], v111, off offset:1792
	global_store_dword v[0:1], v111, off offset:2048
	global_store_dword v[0:1], v111, off offset:2304
	global_store_dword v[0:1], v111, off offset:2560
	global_store_dword v[0:1], v111, off offset:2816
	global_store_dword v[0:1], v111, off offset:3072
	global_store_dword v[0:1], v111, off offset:3328
	global_store_dword v[0:1], v111, off offset:3584
	global_store_dword v[0:1], v111, off offset:3840
